# GEMM phase prologues: K-tile 1's six stage loads issued with K-tile 0's eight before the first wait (vmcnt(8)), one round trip less per phase start
# speedup vs baseline: 1.0227x; 1.0024x over previous
.LBB0_215:
	s_add_i32 m0, s51, 0x18000
	v_lshl_add_u64 v[8:9], v[8:9], 0, s[38:39]
	global_load_lds_dwordx4 v[8:9], off
	v_lshl_add_u64 v[4:5], v[4:5], 0, s[38:39]
	s_add_i32 m0, s51, 0x1a000
	s_add_i32 s91, s51, 0x8000
	global_load_lds_dwordx4 v[4:5], off
	v_lshl_add_u64 v[4:5], v[6:7], 0, s[38:39]
	s_mov_b32 m0, s91
	s_add_i32 s82, s51, 0xa000
	global_load_lds_dwordx4 v[4:5], off
	v_lshl_add_u64 v[4:5], v[10:11], 0, s[38:39]
	s_mov_b32 m0, s82
	v_lshl_add_u64 v[2:3], v[2:3], 0, s[38:39]
	global_load_lds_dwordx4 v[4:5], off
	s_add_i32 m0, s51, 0x1c000
	v_lshl_add_u64 v[0:1], v[0:1], 0, s[38:39]
	global_load_lds_dwordx4 v[2:3], off
	s_add_i32 m0, s51, 0x1e000
	v_bfe_u32 v172, v12, 4, 2
	global_load_lds_dwordx4 v[0:1], off
	s_waitcnt vmcnt(8)
	s_barrier
	s_lshr_b32 s1, s1, 26
	v_and_b32_e32 v173, 15, v12
	s_add_i32 s1, s0, s1
	v_lshlrev_b32_e32 v0, 4, v172
	v_lshlrev_b32_e32 v1, 2, v12
	s_ashr_i32 s16, s1, 6
	v_lshl_or_b32 v0, v173, 6, v0
	s_lshl_b32 s1, s11, 13
	v_and_b32_e32 v1, 32, v1
	v_bitop3_b32 v2, v0, s1, v1 bitop3:0xde
	s_lshl_b32 s1, s18, 5
	s_and_b32 s26, s1, 0x60
	s_lshl_b32 s35, s11, 6
	s_lshl_b32 s1, s26, 7
	s_cmp_gt_i32 s0, 63
	v_bitop3_b32 v174, v0, s1, v1 bitop3:0xde
	s_cselect_b64 s[18:19], -1, 0
	s_add_i32 s83, s16, -2
	v_readlane_b32 s0, v255, 43
	v_add_u32_e32 v0, v15, v13
	s_cmpk_lt_u32 s10, 0x100
	v_readlane_b32 s1, v255, 44
	v_add_lshl_u32 v0, v0, v14, 1
	v_mov_b32_e32 v1, v195
	s_waitcnt vmcnt(6)
	s_cselect_b64 s[22:23], -1, 0
	s_ashr_i32 s42, s50, 31
	s_lshl_b64 s[0:1], s[0:1], 20
	v_readlane_b32 s84, v253, 36
	v_lshl_add_u64 v[142:143], s[8:9], 0, v[0:1]
	v_add_u32_e32 v0, v18, v16
	v_readlane_b32 s85, v253, 37
	s_add_u32 s20, s84, s0
	v_add_lshl_u32 v0, v0, v17, 1
	s_addc_u32 s33, s85, s1
	v_lshl_add_u64 v[144:145], s[8:9], 0, v[0:1]
	s_mov_b32 s43, 0
	v_add_u32_e32 v175, 0, v2
	s_barrier
	v_readlane_b32 s86, v253, 38
	v_readlane_b32 s87, v253, 39
	s_branch .LBB0_218

.LBB0_337:
	s_sext_i32_i8 s83, s10
	s_lshl_b64 s[18:19], s[92:93], 21
	v_readlane_b32 s10, v253, 60
	s_add_u32 s10, s10, s18
	v_readlane_b32 s11, v253, 61
	s_addc_u32 s11, s11, s19
	s_add_i32 m0, s31, 0x18000
	v_lshl_add_u64 v[0:1], v[0:1], 0, s[38:39]
	global_load_lds_dwordx4 v[0:1], off
	v_lshl_add_u64 v[0:1], v[2:3], 0, s[38:39]
	s_add_i32 m0, s31, 0x1a000
	s_add_i32 s50, s31, 0x8000
	global_load_lds_dwordx4 v[0:1], off
	v_lshl_add_u64 v[0:1], v[8:9], 0, s[38:39]
	s_mov_b32 m0, s50
	s_add_i32 s51, s31, 0xa000
	global_load_lds_dwordx4 v[0:1], off
	v_lshl_add_u64 v[0:1], v[10:11], 0, s[38:39]
	s_mov_b32 m0, s51
	v_bfe_u32 v144, v18, 4, 2
	global_load_lds_dwordx4 v[0:1], off
	s_add_i32 m0, s31, 0x1c000
	v_lshl_add_u64 v[0:1], v[4:5], 0, s[38:39]
	global_load_lds_dwordx4 v[0:1], off
	v_lshl_add_u64 v[0:1], v[6:7], 0, s[38:39]
	s_add_i32 m0, s31, 0x1e000
	s_lshr_b32 s1, s1, 26
	global_load_lds_dwordx4 v[0:1], off
	s_waitcnt vmcnt(8)
	s_barrier
	v_and_b32_e32 v145, 15, v18
	s_add_i32 s1, s0, s1
	v_lshlrev_b32_e32 v19, 4, v144
	v_lshlrev_b32_e32 v18, 2, v18
	s_ashr_i32 s43, s1, 6
	v_lshl_or_b32 v19, v145, 6, v19
	s_lshl_b32 s1, s12, 13
	v_and_b32_e32 v18, 32, v18
	v_bitop3_b32 v20, v19, s1, v18 bitop3:0xde
	s_lshl_b32 s1, s13, 5
	s_and_b32 s49, s1, 0x60
	s_lshl_b32 s48, s12, 6
	s_lshl_b32 s1, s49, 7
	s_cmp_gt_i32 s0, 63
	v_readlane_b32 s88, v253, 36
	v_add_u32_e32 v0, v14, v12
	s_cselect_b64 s[12:13], -1, 0
	s_add_i32 s54, s43, -2
	v_readlane_b32 s89, v253, 37
	v_add_lshl_u32 v0, v0, v13, 1
	v_mov_b32_e32 v1, v195
	v_bitop3_b32 v146, v19, s1, v18 bitop3:0xde
	s_waitcnt vmcnt(6)
	s_cmpk_lt_u32 s14, 0x100
	s_mov_b64 s[0:1], s[88:89]
	v_lshl_add_u64 v[134:135], s[4:5], 0, v[0:1]
	v_add_u32_e32 v0, v17, v15
	s_cselect_b64 s[14:15], -1, 0
	s_add_u32 s55, s0, s18
	v_add_lshl_u32 v0, v0, v16, 1
	s_addc_u32 s68, s1, s19
	v_lshl_add_u64 v[136:137], s[4:5], 0, v[0:1]
	s_mov_b32 s69, 0
	v_add_u32_e32 v147, 0, v20
	s_barrier
	v_readlane_b32 s90, v253, 38
	v_readlane_b32 s91, v253, 39
	s_branch .LBB0_340

.LBB0_556:
	v_bfe_u32 v166, v6, 4, 2
	s_lshr_b32 s1, s1, 26
	v_and_b32_e32 v167, 15, v6
	s_add_i32 s1, s0, s1
	v_lshlrev_b32_e32 v7, 4, v166
	v_lshlrev_b32_e32 v6, 2, v6
	s_ashr_i32 s26, s1, 6
	v_lshl_or_b32 v7, v167, 6, v7
	s_lshl_b32 s1, s15, 13
	v_and_b32_e32 v6, 32, v6
	v_bitop3_b32 v20, v7, s1, v6 bitop3:0xde
	s_lshl_b32 s1, s14, 5
	s_and_b32 s35, s1, 0x60
	v_lshl_add_u64 v[8:9], s[28:29], 0, v[194:195]
	v_mov_b32_e32 v145, v195
	s_lshl_b32 s1, s35, 7
	v_lshl_add_u64 v[10:11], s[28:29], 0, v[144:145]
	v_mov_b32_e32 v149, v195
	v_bitop3_b32 v168, v7, s1, v6 bitop3:0xde
	s_add_i32 m0, s6, 0x18000
	v_lshl_add_u64 v[6:7], v[8:9], 0, s[38:39]
	v_lshl_add_u64 v[16:17], s[24:25], 0, v[148:149]
	v_mov_b32_e32 v147, v195
	global_load_lds_dwordx4 v[6:7], off
	v_lshl_add_u64 v[6:7], v[10:11], 0, s[38:39]
	s_add_i32 m0, s6, 0x1a000
	s_add_i32 s42, s6, 0x8000
	v_lshl_add_u64 v[18:19], s[24:25], 0, v[146:147]
	global_load_lds_dwordx4 v[6:7], off
	v_lshl_add_u64 v[6:7], v[16:17], 0, s[38:39]
	s_mov_b32 m0, s42
	s_add_i32 s43, s6, 0xa000
	v_lshl_add_u64 v[12:13], s[4:5], 0, v[194:195]
	global_load_lds_dwordx4 v[6:7], off
	v_lshl_add_u64 v[6:7], v[18:19], 0, s[38:39]
	s_mov_b32 m0, s43
	v_lshl_add_u64 v[14:15], s[4:5], 0, v[144:145]
	global_load_lds_dwordx4 v[6:7], off
	s_add_i32 m0, s6, 0x1c000
	v_lshl_add_u64 v[6:7], v[12:13], 0, s[38:39]
	global_load_lds_dwordx4 v[6:7], off
	v_lshl_add_u64 v[6:7], v[14:15], 0, s[38:39]
	s_add_i32 m0, s6, 0x1e000
	s_lshl_b32 s33, s15, 6
	global_load_lds_dwordx4 v[6:7], off
	s_waitcnt vmcnt(8)
	s_barrier
	s_cmp_gt_i32 s0, 63
	s_waitcnt vmcnt(6)
	s_cselect_b64 s[14:15], -1, 0
	s_add_i32 s48, s26, -2
	v_add_u32_e32 v3, v5, v3
	v_add_u32_e32 v0, v2, v0
	s_cmpk_lt_u32 s18, 0x100
	v_add_lshl_u32 v4, v3, v4, 1
	v_mov_b32_e32 v5, v195
	v_add_lshl_u32 v0, v0, v1, 1
	v_mov_b32_e32 v1, v195
	s_cselect_b64 s[18:19], -1, 0
	v_lshl_add_u64 v[150:151], s[8:9], 0, v[4:5]
	v_lshl_add_u64 v[152:153], s[8:9], 0, v[0:1]
	s_mov_b32 s49, 0
	v_add_u32_e32 v169, 0, v20
	v_readlane_b32 s55, v254, 58
	v_readlane_b32 s54, v254, 61
	s_barrier
	s_branch .LBB0_559

.LBB0_665:
	v_bfe_u32 v184, v6, 4, 2
	s_lshr_b32 s1, s1, 26
	v_and_b32_e32 v185, 15, v6
	s_add_i32 s1, s0, s1
	v_lshlrev_b32_e32 v7, 4, v184
	v_lshlrev_b32_e32 v6, 2, v6
	s_and_b32 s31, s19, 3
	s_ashr_i32 s33, s1, 6
	v_lshl_or_b32 v7, v185, 6, v7
	s_lshl_b32 s1, s18, 13
	v_and_b32_e32 v6, 32, v6
	v_lshl_add_u64 v[8:9], s[28:29], 0, v[194:195]
	v_mov_b32_e32 v157, v195
	v_bitop3_b32 v20, v7, s1, v6 bitop3:0xde
	s_lshl_b32 s1, s31, 12
	v_lshl_add_u64 v[10:11], s[28:29], 0, v[156:157]
	v_mov_b32_e32 v161, v195
	v_bitop3_b32 v186, v7, s1, v6 bitop3:0xde
	s_add_i32 m0, s16, 0x18000
	v_lshl_add_u64 v[6:7], v[8:9], 0, s[38:39]
	v_lshl_add_u64 v[16:17], s[24:25], 0, v[160:161]
	v_mov_b32_e32 v159, v195
	global_load_lds_dwordx4 v[6:7], off
	v_lshl_add_u64 v[6:7], v[10:11], 0, s[38:39]
	s_add_i32 m0, s16, 0x1a000
	s_add_i32 s43, s16, 0x8000
	v_lshl_add_u64 v[18:19], s[24:25], 0, v[158:159]
	global_load_lds_dwordx4 v[6:7], off
	v_lshl_add_u64 v[6:7], v[16:17], 0, s[38:39]
	s_mov_b32 m0, s43
	s_add_i32 s48, s16, 0xa000
	v_lshl_add_u64 v[12:13], s[4:5], 0, v[194:195]
	global_load_lds_dwordx4 v[6:7], off
	v_lshl_add_u64 v[6:7], v[18:19], 0, s[38:39]
	s_mov_b32 m0, s48
	v_lshl_add_u64 v[14:15], s[4:5], 0, v[156:157]
	global_load_lds_dwordx4 v[6:7], off
	s_add_i32 m0, s16, 0x1c000
	v_lshl_add_u64 v[6:7], v[12:13], 0, s[38:39]
	global_load_lds_dwordx4 v[6:7], off
	v_lshl_add_u64 v[6:7], v[14:15], 0, s[38:39]
	s_add_i32 m0, s16, 0x1e000
	s_lshl_b32 s35, s18, 6
	global_load_lds_dwordx4 v[6:7], off
	s_waitcnt vmcnt(8)
	s_barrier
	s_lshl_b32 s42, s31, 5
	s_cmp_gt_i32 s0, 63
	s_waitcnt vmcnt(6)
	s_cselect_b64 s[18:19], -1, 0
	s_add_i32 s49, s33, -2
	v_add_u32_e32 v3, v5, v3
	v_add_u32_e32 v0, v2, v0
	s_cmpk_lt_u32 s22, 0x100
	v_add_lshl_u32 v4, v3, v4, 1
	v_mov_b32_e32 v5, v195
	v_add_lshl_u32 v0, v0, v1, 1
	v_mov_b32_e32 v1, v195
	s_cselect_b64 s[22:23], -1, 0
	v_lshl_add_u64 v[162:163], s[8:9], 0, v[4:5]
	v_lshl_add_u64 v[164:165], s[8:9], 0, v[0:1]
	s_mov_b32 s50, 0
	v_add_u32_e32 v187, 0, v20
	v_readlane_b32 s55, v254, 58
	v_readlane_b32 s72, v254, 61
	s_barrier
	s_branch .LBB0_668

.LBB0_767:
	v_bfe_u32 v147, v6, 4, 2
	s_lshr_b32 s1, s1, 26
	v_and_b32_e32 v149, 15, v6
	s_add_i32 s1, s0, s1
	v_lshlrev_b32_e32 v7, 4, v147
	v_lshlrev_b32_e32 v6, 2, v6
	s_ashr_i32 s31, s1, 6
	v_lshl_or_b32 v7, v149, 6, v7
	s_lshl_b32 s1, s19, 13
	v_and_b32_e32 v6, 32, v6
	v_bitop3_b32 v20, v7, s1, v6 bitop3:0xde
	s_lshl_b32 s1, s18, 5
	s_and_b32 s35, s1, 0x60
	v_lshl_add_u64 v[8:9], s[24:25], 0, v[194:195]
	v_mov_b32_e32 v133, v195
	s_lshl_b32 s1, s35, 7
	v_lshl_add_u64 v[10:11], s[24:25], 0, v[132:133]
	v_mov_b32_e32 v137, v195
	v_bitop3_b32 v155, v7, s1, v6 bitop3:0xde
	s_add_i32 m0, s16, 0x18000
	v_lshl_add_u64 v[6:7], v[8:9], 0, s[38:39]
	v_lshl_add_u64 v[16:17], s[28:29], 0, v[136:137]
	v_mov_b32_e32 v135, v195
	global_load_lds_dwordx4 v[6:7], off
	v_lshl_add_u64 v[6:7], v[10:11], 0, s[38:39]
	s_add_i32 m0, s16, 0x1a000
	s_add_i32 s42, s16, 0x8000
	v_lshl_add_u64 v[18:19], s[28:29], 0, v[134:135]
	global_load_lds_dwordx4 v[6:7], off
	v_lshl_add_u64 v[6:7], v[16:17], 0, s[38:39]
	s_mov_b32 m0, s42
	s_add_i32 s43, s16, 0xa000
	v_lshl_add_u64 v[12:13], s[4:5], 0, v[194:195]
	global_load_lds_dwordx4 v[6:7], off
	v_lshl_add_u64 v[6:7], v[18:19], 0, s[38:39]
	s_mov_b32 m0, s43
	v_lshl_add_u64 v[14:15], s[4:5], 0, v[132:133]
	global_load_lds_dwordx4 v[6:7], off
	s_add_i32 m0, s16, 0x1c000
	v_lshl_add_u64 v[6:7], v[12:13], 0, s[38:39]
	global_load_lds_dwordx4 v[6:7], off
	v_lshl_add_u64 v[6:7], v[14:15], 0, s[38:39]
	s_add_i32 m0, s16, 0x1e000
	s_lshl_b32 s33, s19, 6
	global_load_lds_dwordx4 v[6:7], off
	s_waitcnt vmcnt(8)
	s_barrier
	s_cmp_gt_i32 s0, 63
	s_waitcnt vmcnt(6)
	s_cselect_b64 s[18:19], -1, 0
	s_add_i32 s48, s31, -2
	v_add_u32_e32 v3, v5, v3
	v_add_u32_e32 v0, v2, v0
	s_cmpk_lt_u32 s22, 0x100
	v_add_lshl_u32 v4, v3, v4, 1
	v_mov_b32_e32 v5, v195
	v_add_lshl_u32 v0, v0, v1, 1
	v_mov_b32_e32 v1, v195
	s_cselect_b64 s[22:23], -1, 0
	v_lshl_add_u64 v[138:139], s[8:9], 0, v[4:5]
	v_lshl_add_u64 v[140:141], s[8:9], 0, v[0:1]
	s_mov_b32 s49, 0
	v_add_u32_e32 v159, 0, v20
	v_readlane_b32 s54, v255, 10
	v_readlane_b32 s55, v255, 8
	s_barrier
	s_branch .LBB0_770

.LBB0_1040:
	v_bfe_u32 v184, v6, 4, 2
	s_lshr_b32 s1, s1, 26
	v_and_b32_e32 v185, 15, v6
	s_add_i32 s1, s0, s1
	v_lshlrev_b32_e32 v7, 4, v184
	v_lshlrev_b32_e32 v6, 2, v6
	s_and_b32 s26, s23, 3
	s_ashr_i32 s30, s1, 6
	v_lshl_or_b32 v7, v185, 6, v7
	s_lshl_b32 s1, s22, 13
	v_and_b32_e32 v6, 32, v6
	v_lshl_add_u64 v[8:9], s[28:29], 0, v[194:195]
	v_mov_b32_e32 v157, v195
	v_bitop3_b32 v20, v7, s1, v6 bitop3:0xde
	s_lshl_b32 s1, s26, 12
	v_lshl_add_u64 v[10:11], s[28:29], 0, v[156:157]
	v_mov_b32_e32 v161, v195
	v_bitop3_b32 v186, v7, s1, v6 bitop3:0xde
	s_add_i32 m0, s6, 0x18000
	v_lshl_add_u64 v[6:7], v[8:9], 0, s[38:39]
	v_lshl_add_u64 v[16:17], s[24:25], 0, v[160:161]
	v_mov_b32_e32 v159, v195
	global_load_lds_dwordx4 v[6:7], off
	v_lshl_add_u64 v[6:7], v[10:11], 0, s[38:39]
	s_add_i32 m0, s6, 0x1a000
	s_add_i32 s35, s6, 0x8000
	v_lshl_add_u64 v[18:19], s[24:25], 0, v[158:159]
	global_load_lds_dwordx4 v[6:7], off
	v_lshl_add_u64 v[6:7], v[16:17], 0, s[38:39]
	s_mov_b32 m0, s35
	s_add_i32 s42, s6, 0xa000
	v_lshl_add_u64 v[12:13], s[4:5], 0, v[194:195]
	global_load_lds_dwordx4 v[6:7], off
	v_lshl_add_u64 v[6:7], v[18:19], 0, s[38:39]
	s_mov_b32 m0, s42
	v_lshl_add_u64 v[14:15], s[4:5], 0, v[156:157]
	global_load_lds_dwordx4 v[6:7], off
	s_add_i32 m0, s6, 0x1c000
	v_lshl_add_u64 v[6:7], v[12:13], 0, s[38:39]
	global_load_lds_dwordx4 v[6:7], off
	v_lshl_add_u64 v[6:7], v[14:15], 0, s[38:39]
	s_add_i32 m0, s6, 0x1e000
	s_lshl_b32 s31, s22, 6
	global_load_lds_dwordx4 v[6:7], off
	s_waitcnt vmcnt(8)
	s_barrier
	s_lshl_b32 s33, s26, 5
	s_cmp_gt_i32 s0, 63
	s_waitcnt vmcnt(6)
	s_cselect_b64 s[22:23], -1, 0
	s_add_i32 s43, s30, -2
	v_add_u32_e32 v3, v5, v3
	v_add_u32_e32 v0, v2, v0
	s_cmpk_lt_u32 s48, 0x100
	v_add_lshl_u32 v4, v3, v4, 1
	v_mov_b32_e32 v5, v195
	v_add_lshl_u32 v0, v0, v1, 1
	v_mov_b32_e32 v1, v195
	s_cselect_b64 s[68:69], -1, 0
	v_lshl_add_u64 v[162:163], s[10:11], 0, v[4:5]
	v_lshl_add_u64 v[164:165], s[10:11], 0, v[0:1]
	s_mov_b32 s48, 0
	v_add_u32_e32 v187, 0, v20
	v_readlane_b32 s51, v254, 58
	v_readlane_b32 s54, v254, 61
	s_barrier
	s_branch .LBB0_1043

.LBB0_1138:
	v_bfe_u32 v140, v6, 4, 2
	s_lshr_b32 s1, s1, 26
	v_and_b32_e32 v141, 15, v6
	s_add_i32 s1, s0, s1
	v_lshlrev_b32_e32 v7, 4, v140
	v_lshlrev_b32_e32 v6, 2, v6
	s_ashr_i32 s35, s1, 6
	v_lshl_or_b32 v7, v141, 6, v7
	s_lshl_b32 s1, s19, 13
	v_and_b32_e32 v6, 32, v6
	v_bitop3_b32 v20, v7, s1, v6 bitop3:0xde
	s_lshl_b32 s1, s18, 5
	s_and_b32 s43, s1, 0x60
	v_lshl_add_u64 v[8:9], s[48:49], 0, v[194:195]
	v_mov_b32_e32 v129, v195
	s_lshl_b32 s1, s43, 7
	v_lshl_add_u64 v[10:11], s[48:49], 0, v[128:129]
	v_mov_b32_e32 v133, v195
	v_bitop3_b32 v142, v7, s1, v6 bitop3:0xde
	s_add_i32 m0, s16, 0x18000
	v_lshl_add_u64 v[6:7], v[8:9], 0, s[38:39]
	v_lshl_add_u64 v[16:17], s[28:29], 0, v[132:133]
	v_mov_b32_e32 v131, v195
	global_load_lds_dwordx4 v[6:7], off
	v_lshl_add_u64 v[6:7], v[10:11], 0, s[38:39]
	s_add_i32 m0, s16, 0x1a000
	s_add_i32 s50, s16, 0x8000
	v_lshl_add_u64 v[18:19], s[28:29], 0, v[130:131]
	global_load_lds_dwordx4 v[6:7], off
	v_lshl_add_u64 v[6:7], v[16:17], 0, s[38:39]
	s_mov_b32 m0, s50
	s_add_i32 s51, s16, 0xa000
	v_lshl_add_u64 v[12:13], s[4:5], 0, v[194:195]
	global_load_lds_dwordx4 v[6:7], off
	v_lshl_add_u64 v[6:7], v[18:19], 0, s[38:39]
	s_mov_b32 m0, s51
	v_lshl_add_u64 v[14:15], s[4:5], 0, v[128:129]
	global_load_lds_dwordx4 v[6:7], off
	s_add_i32 m0, s16, 0x1c000
	v_lshl_add_u64 v[6:7], v[12:13], 0, s[38:39]
	global_load_lds_dwordx4 v[6:7], off
	v_lshl_add_u64 v[6:7], v[14:15], 0, s[38:39]
	s_add_i32 m0, s16, 0x1e000
	s_lshl_b32 s42, s19, 6
	global_load_lds_dwordx4 v[6:7], off
	s_waitcnt vmcnt(8)
	s_barrier
	s_cmp_gt_i32 s0, 63
	s_waitcnt vmcnt(6)
	s_cselect_b64 s[18:19], -1, 0
	s_add_i32 s54, s35, -2
	v_add_u32_e32 v3, v5, v3
	v_add_u32_e32 v0, v2, v0
	s_cmpk_lt_u32 s22, 0x100
	v_add_lshl_u32 v4, v3, v4, 1
	v_mov_b32_e32 v5, v195
	v_add_lshl_u32 v0, v0, v1, 1
	v_mov_b32_e32 v1, v195
	s_cselect_b64 s[22:23], -1, 0
	v_lshl_add_u64 v[134:135], s[8:9], 0, v[4:5]
	v_lshl_add_u64 v[136:137], s[8:9], 0, v[0:1]
	s_mov_b32 s55, 0
	v_add_u32_e32 v143, 0, v20
	v_readlane_b32 s73, v255, 16
	v_readlane_b32 s72, v255, 14
	s_barrier
	s_branch .LBB0_1141

.LBB0_1211:
	v_bfe_u32 v205, v6, 4, 2
	s_lshr_b32 s1, s1, 26
	v_and_b32_e32 v228, 15, v6
	s_add_i32 s1, s0, s1
	v_lshlrev_b32_e32 v7, 4, v205
	v_lshlrev_b32_e32 v6, 2, v6
	s_and_b32 s49, s20, 3
	s_ashr_i32 s50, s1, 6
	v_lshl_or_b32 v7, v228, 6, v7
	s_lshl_b32 s1, s16, 13
	v_and_b32_e32 v6, 32, v6
	v_lshl_add_u64 v[8:9], s[10:11], 0, v[194:195]
	v_mov_b32_e32 v161, v195
	v_bitop3_b32 v20, v7, s1, v6 bitop3:0xde
	s_lshl_b32 s1, s49, 12
	v_lshl_add_u64 v[10:11], s[10:11], 0, v[160:161]
	v_mov_b32_e32 v165, v195
	v_bitop3_b32 v229, v7, s1, v6 bitop3:0xde
	s_add_i32 m0, s29, 0x18000
	v_lshl_add_u64 v[6:7], v[8:9], 0, s[38:39]
	v_lshl_add_u64 v[16:17], s[24:25], 0, v[164:165]
	v_mov_b32_e32 v163, v195
	global_load_lds_dwordx4 v[6:7], off
	v_lshl_add_u64 v[6:7], v[10:11], 0, s[38:39]
	s_add_i32 m0, s29, 0x1a000
	s_add_i32 s55, s29, 0x8000
	v_lshl_add_u64 v[18:19], s[24:25], 0, v[162:163]
	global_load_lds_dwordx4 v[6:7], off
	v_lshl_add_u64 v[6:7], v[16:17], 0, s[38:39]
	s_mov_b32 m0, s55
	s_add_i32 s88, s29, 0xa000
	v_lshl_add_u64 v[12:13], s[4:5], 0, v[194:195]
	global_load_lds_dwordx4 v[6:7], off
	v_lshl_add_u64 v[6:7], v[18:19], 0, s[38:39]
	s_mov_b32 m0, s88
	v_lshl_add_u64 v[14:15], s[4:5], 0, v[160:161]
	global_load_lds_dwordx4 v[6:7], off
	s_add_i32 m0, s29, 0x1c000
	v_lshl_add_u64 v[6:7], v[12:13], 0, s[38:39]
	global_load_lds_dwordx4 v[6:7], off
	v_lshl_add_u64 v[6:7], v[14:15], 0, s[38:39]
	s_add_i32 m0, s29, 0x1e000
	s_lshl_b32 s51, s16, 6
	global_load_lds_dwordx4 v[6:7], off
	s_waitcnt vmcnt(8)
	s_barrier
	s_lshl_b32 s54, s49, 5
	s_cmp_gt_i32 s0, 63
	s_waitcnt vmcnt(6)
	s_cselect_b64 s[22:23], -1, 0
	s_add_i32 s89, s50, -2
	v_add_u32_e32 v3, v5, v3
	v_add_u32_e32 v0, v2, v0
	s_cmpk_lt_u32 s3, 0x100
	v_add_lshl_u32 v4, v3, v4, 1
	v_mov_b32_e32 v5, v195
	v_add_lshl_u32 v0, v0, v1, 1
	v_mov_b32_e32 v1, v195
	s_cselect_b64 s[68:69], -1, 0
	v_lshl_add_u64 v[166:167], s[8:9], 0, v[4:5]
	v_lshl_add_u64 v[168:169], s[8:9], 0, v[0:1]
	s_mov_b32 s3, 0
	v_add_u32_e32 v230, 0, v20
	v_readlane_b32 s16, v254, 58
	v_readlane_b32 s20, v254, 61
	s_barrier
	s_branch .LBB0_1214
